# v60 + per-workgroup start skew (8 groups x ~0.6us) in the w1 phases to de-synchronise the nt epilogue store bursts
# baseline (speedup 1.0000x reference)
; __device__ __forceinline__ int bid_o() { int t = (int)blockIdx.x; asm volatile("" : "+s"(t)); return t; }
;     __device__ void init(int G_, int c_, int trim_) { lat.init(16384, 6656, G_, c_); G = G_; c = c_; trim = trim_; ncc = trim_ ? 14 : 26; }
; __device__ __forceinline__ void run_phase(KParams p, int ph, LAS unsigned char* lds) {
;     ...
;     switch (s) {
;     case 0: case 5: norm_phase(p, l, s == 5 ? 1 : 0, s == 5 ? Mx : MT); break;
;     case 1: { pg8::EpiBf16<0> E; E.O = p->big; E.ldc = NIN; pg8::InOrder S; S.init((int)gridDim.x, bid_o(), l == 1); run_gemm_s(lds, p->h, wt + WT_IN, MT, NIN, DM, DM, S, E);
;               if (l == 0 && bid_o() >= 80) {
;                   const int b2 = bid_o() - 80; const int n_it = (2048 - b2 + 175) / 176;
;                   transpose_tiles(p, lds, n_it, [&](int k) { return 4224 + b2 + 176 * k; }); } } break;
;     case 2: hgA_phase(p, l, lds); break;
;     case 3: mixer_phase(p, l, lds); break;
;     case 4: { pg8::EpiRes E; E.src_lat = (l == 0) ? p->x : p->out; E.src_ctx = (l == 0) ? p->ctx : p->xc; E.dst_lat = p->out; E.dst_ctx = p->xc; E.gate = modl + 4096;
;               run_gemm(lds, p->mix, wt + WT_OUT, ML, DM, DM, E);
;               if (l == 0) {
;                   pg8::EpiPart EP; EP.part = (float*)p->big; EP.Mp = MC; EP.ldc = DM;
;                   pg8::SplitOrder S; S.init(MC, DM, 4, (int)gridDim.x, bid_o());
;                   run_gemm_s(lds, p->mix + (size_t)ML * DM, wt + WT_OUT, MC, DM, DM / 4, DM, S, EP); } } break;
;     case 6: { pg8::EpiBf16<1> E; E.O = p->big; E.ldc = HID; run_gemm(lds, p->h, wt + WT_1, Mx, HID, DM, E); } break;
; __global__ void __launch_bounds__(512, 2) mega(Params p_arg, int ph_lo, int ph_hi) {
;     ...
;     for (int ph = ph_lo; ph < ph_hi; ++ph) {
;         KParams p = (KParams)__builtin_amdgcn_kernarg_segment_ptr();
;         asm volatile("" : "+s"(p));
;         run_phase(p, ph, lds);
.Lsprio_skip:
	s_mov_b32 s101, 0
	s_cmp_eq_u32 s98, 6
	s_cselect_b32 s101, 1, s101
	s_bfe_u32 s100, s94, 0x30003
	s_mul_i32 s100, s100, s101
	s_cmp_eq_u32 s100, 0
	s_cbranch_scc1 .Lskew_done
.Lskew_loop:
	s_sleep 18
	s_add_i32 s100, s100, -1
	s_cmp_lg_u32 s100, 0
	s_cbranch_scc1 .Lskew_loop
